# SSD state update reads its B^T fragments with ds_read_b64_tr_b16 straight from the row-major B tile; the transposed LDS copy (32 VALU + 4 LDS writes per chunk on the critical waves) is gone
# speedup vs baseline: 1.0053x; 1.0053x over previous
.LBB0_349:
	s_waitcnt vmcnt(5)
	v_cndmask_b32_e64 v4, 0, v4, s[0:1]
	v_cndmask_b32_e64 v5, 0, v5, s[0:1]
	v_cndmask_b32_e64 v6, 0, v6, s[0:1]
	v_cndmask_b32_e64 v7, 0, v7, s[0:1]
	s_waitcnt vmcnt(4)
	v_cndmask_b32_e64 v8, 0, v8, s[0:1]
	v_cndmask_b32_e64 v9, 0, v9, s[0:1]
	v_cndmask_b32_e64 v10, 0, v10, s[0:1]
	v_cndmask_b32_e64 v11, 0, v11, s[0:1]
	s_waitcnt vmcnt(3)
	v_cndmask_b32_e64 v12, 0, v12, s[0:1]
	v_cndmask_b32_e64 v13, 0, v13, s[0:1]
	v_cndmask_b32_e64 v14, 0, v14, s[0:1]
	v_cndmask_b32_e64 v15, 0, v15, s[0:1]
	s_waitcnt vmcnt(2)
	v_cndmask_b32_e64 v20, 0, v16, s[0:1]
	v_cndmask_b32_e64 v21, 0, v17, s[0:1]
	v_cndmask_b32_e64 v22, 0, v18, s[0:1]
	v_cndmask_b32_e64 v23, 0, v19, s[0:1]
	s_or_b32 s37, s85, 64
	v_readlane_b32 s0, v252, 52
	s_add_u32 s62, s0, s72
	v_readlane_b32 s0, v254, 27
	v_cmp_lt_i32_e32 vcc, -5, v48
	v_readlane_b32 s1, v252, 53
	v_mov_b32_e32 v2, s0
	v_cndmask_b32_e32 v17, 0, v25, vcc
	v_cndmask_b32_e32 v25, 0, v29, vcc
	v_cndmask_b32_e32 v29, 0, v33, vcc
	v_cndmask_b32_e32 v33, 0, v37, vcc
	v_cndmask_b32_e64 v2, 0, v2, s[38:39]
	s_movk_i32 s0, 0x440
	v_or_b32_e32 v37, 1, v50
	s_movk_i32 s3, 0x110
	v_cndmask_b32_e64 v58, 0, v40, s[40:41]
	v_cndmask_b32_e64 v59, 0, v41, s[40:41]
	s_addc_u32 s63, s1, 0
	v_mad_u64_u32 v[40:41], s[0:1], v48, s0, v[2:3]
	v_mad_u64_u32 v[70:71], s[0:1], v37, s3, v[2:3]
	s_movk_i32 s0, 0x6800
	s_nop 0
	v_mul_lo_u32 v72, v48, s0
	s_movk_i32 s0, 0x120
	v_cndmask_b32_e32 v16, 0, v24, vcc
	v_cndmask_b32_e32 v24, 0, v28, vcc
	v_cndmask_b32_e32 v28, 0, v32, vcc
	v_cndmask_b32_e32 v32, 0, v36, vcc
	v_and_b32_e32 v36, 15, v51
	v_lshl_or_b32 v64, v94, 2, s23
	s_movk_i32 s2, 0x1a00
	v_mul_lo_u32 v96, v49, s0
	v_or_b32_e32 v2, 1, v55
	s_add_i32 s0, 0, 0x1a400
	s_add_i32 s1, 0, 0x1a600
	s_add_i32 s23, 0, 0x18000
	s_movk_i32 s25, 0x480
	v_lshl_or_b32 v62, v36, 3, v54
	v_lshlrev_b32_e32 v95, 4, v36
	v_mul_lo_u32 v97, v2, s71
	v_mul_lo_u32 v82, v2, s2
	s_cmp_lt_u32 s30, 32
	v_bitop3_b32 v2, v48, v1, 14 bitop3:0x78
	v_mad_u32_u24 v102, v36, s25, 0
	v_lshlrev_b32_e32 v36, 2, v65
	v_readlane_b32 s42, v252, 44
	v_cndmask_b32_e32 v18, 0, v26, vcc
	v_cndmask_b32_e32 v19, 0, v27, vcc
	v_cndmask_b32_e32 v26, 0, v30, vcc
	v_cndmask_b32_e32 v27, 0, v31, vcc
	v_cndmask_b32_e32 v30, 0, v34, vcc
	v_cndmask_b32_e32 v31, 0, v35, vcc
	v_cndmask_b32_e32 v34, 0, v38, vcc
	v_cndmask_b32_e32 v35, 0, v39, vcc
	v_cmp_lt_i32_e32 vcc, -9, v49
	s_cselect_b64 s[64:65], -1, 0
	v_lshlrev_b32_e32 v100, 3, v2
	v_readlane_b32 s43, v252, 45
	s_add_u32 s66, s42, s72
	v_or_b32_e32 v2, 0x100, v36
	v_cndmask_b32_e32 v69, 0, v47, vcc
	s_addc_u32 s67, s43, 0
	v_add_u32_e32 v104, s0, v2
	v_add_u32_e32 v105, s1, v2
	v_or_b32_e32 v47, s27, v94
	v_mov_b32_e32 v2, s23
	s_lshl_b32 s22, s22, 1
	v_lshrrev_b32_e32 v38, 4, v65
	v_mad_u32_u24 v108, v47, s71, v2
	v_lshrrev_b32_e32 v2, 3, v94
	s_and_b32 s22, s22, 6
	v_or_b32_e32 v51, s22, v2
	v_bitop3_b32 v2, s22, v38, v2 bitop3:0x36
	s_lshl_b32 s22, s21, 6
	v_lshlrev_b32_e32 v54, 4, v2
	v_or_b32_e32 v2, s22, v94
	v_mul_lo_u32 v2, v2, s71
	v_cndmask_b32_e64 v61, 0, v43, s[40:41]
	v_lshlrev_b32_e32 v39, 2, v55
	v_lshlrev_b32_e32 v43, 1, v1
	v_add_u32_e32 v55, 0, v2
	v_lshlrev_b32_e32 v2, 3, v38
	v_lshl_or_b32 v38, v38, 2, s27
	v_bitop3_b32 v43, v43, v49, 28 bitop3:0x6c
	v_or_b32_e32 v110, 2, v38
	v_mul_lo_u32 v74, v37, s2
	v_lshlrev_b32_e32 v37, 3, v94
	v_readlane_b32 s4, v254, 28
	v_lshlrev_b32_e32 v43, 2, v43
	v_readlane_b32 s2, v254, 30
	v_mad_u32_u24 v106, v47, s3, 0
	v_and_b32_e32 v107, 48, v1
	v_mul_lo_u32 v48, v86, s3
	s_lshl_b32 s25, s20, 6
	v_cmp_gt_i32_e64 s[46:47], v110, v86
	v_or_b32_e32 v110, 3, v38
	v_readlane_b32 s3, v254, 31
	v_lshlrev_b32_e32 v51, 4, v51
	s_lshl_b32 s20, s20, 8
	v_cndmask_b32_e32 v67, 0, v45, vcc
	v_add_u32_e32 v71, s4, v37
	v_readlane_b32 s5, v254, 29
	v_add_u32_e32 v45, s23, v43
	v_add_u32_e32 v101, s2, v36
	s_and_b32 s23, s22, 64
	v_lshlrev_b32_e32 v120, 2, v86
	v_cmp_gt_i32_e64 s[42:43], v38, v86
	v_cmp_lt_i32_e64 s[44:45], v38, v86
	v_cmp_gt_i32_e64 s[48:49], v110, v86
	v_mul_lo_u32 v150, v86, s71
	s_add_i32 s27, s26, s3
	v_lshlrev_b32_e32 v121, 2, v87
	v_cmp_gt_i32_e64 s[50:51], v38, v87
	v_cmp_lt_i32_e64 s[52:53], v38, v87
	v_add_u32_e32 v87, 14, v86
	v_add_u32_e32 v86, 13, v86
	v_bitop3_b32 v111, v51, v107, 64 bitop3:0x1e
	v_add_u32_e32 v151, s3, v107
	v_bitop3_b32 v113, v51, v1, 48 bitop3:0x78
	v_lshl_add_u32 v51, s21, 7, v106
	s_add_i32 s21, s26, s4
	s_add_i32 s20, s2, s20
	v_readlane_b32 s2, v254, 32
	v_readlane_b32 s3, v254, 33
	v_readlane_b32 s4, v254, 35
	v_cndmask_b32_e64 v60, 0, v42, s[40:41]
	v_cmp_gt_i32_e64 s[40:41], 64, v1
	v_or_b32_e32 v50, 64, v107
	v_bitop3_b32 v91, s23, v1, 48 bitop3:0x72
	v_cmp_gt_i32_e64 s[54:55], v38, v87
	v_cmp_gt_i32_e64 s[56:57], v38, v86
	v_add_u32_e32 v38, 0x900, v150
	v_mov_b32_e32 v86, s5
	v_add_u32_e32 v116, s3, v39
	v_readlane_b32 s3, v254, 34
	v_mov_b32_e32 v1, s4
	s_add_i32 s26, s26, s2
	v_cndmask_b32_e32 v66, 0, v44, vcc
	v_cndmask_b32_e32 v68, 0, v46, vcc
	v_add_u32_e32 v41, 0x110, v70
	v_add_u32_e32 v42, 0x220, v70
	v_add_u32_e32 v98, s0, v39
	v_add_u32_e32 v99, s1, v39
	v_add_u32_e32 v44, s5, v43
	v_mul_u32_u24_e32 v46, 0x240, v94
	v_mul_lo_u32 v80, v49, s29
	v_add_u32_e32 v49, 0, v107
	v_and_b32_e32 v92, 48, v65
	v_add_u32_e32 v145, s27, v38
	v_bitop3_b32 v147, s23, v50, 16 bitop3:0x36
	v_bitop3_b32 v148, s23, v50, 32 bitop3:0x36
	v_bitop3_b32 v50, s23, v50, 48 bitop3:0x36
	v_mad_u32_u24 v112, v47, s71, v86
	v_add_u32_e32 v129, s21, v38
	v_add_u32_e32 v117, s3, v39
	v_add_u32_e32 v43, s4, v43
	v_mad_u32_u24 v122, v47, s71, v1
	v_add_u32_e32 v47, s26, v150
	v_add_u32_e32 v133, s26, v38
	v_mov_b32_e32 v38, v3
	v_mov_b32_e32 v39, v3
	v_add_u32_e32 v76, 0x1a00, v74
	v_add_u32_e32 v78, 0x3400, v74
	v_add_u32_e32 v88, s23, v55
	v_bitop3_b32 v89, s23, v107, 16 bitop3:0x36
	v_bitop3_b32 v90, s23, v107, 32 bitop3:0x36
	v_add_u32_e32 v93, s1, v92
	v_add_u32_e32 v144, s27, v150
	v_bitop3_b32 v146, s22, v107, 64 bitop3:0x4e
	v_add_u32_e32 v128, s21, v150
	v_lshl_add_u64 v[86:87], s[74:75], 0, v[2:3]
	s_add_i32 s74, s24, s85
	v_add_u32_e32 v115, s2, v37
	v_add_u32_e32 v118, s0, v36
	v_add_u32_e32 v119, s1, v36
	v_add_u32_e32 v92, s3, v92
	v_mov_b32_e32 v36, v3
	v_mov_b32_e32 v37, v3
	v_add_u32_e32 v126, v44, v46
	v_add_u32_e32 v130, v43, v46
	v_add_u32_e32 v132, v47, v2
	v_add_u32_e32 v134, v40, v95
	v_add_u32_e32 v135, v41, v95
	v_add_u32_e32 v136, v42, v95
	v_add_u32_e32 v137, v45, v46
	v_add_u32_e32 v138, v49, v48
	v_add_u32_e32 v149, v55, v50
	v_add_u32_e32 v150, v151, v150
	v_add_u32_e32 v151, v51, v2
	v_mov_b64_e32 v[46:47], v[38:39]
	v_mov_b64_e32 v[42:43], v[38:39]
	v_mov_b64_e32 v[50:51], v[38:39]
	s_mov_b32 s36, 0
	s_mov_b32 s78, 1
	v_ashrrev_i32_e32 v73, 31, v72
	v_ashrrev_i32_e32 v75, 31, v74
	v_ashrrev_i32_e32 v77, 31, v76
	v_ashrrev_i32_e32 v79, 31, v78
	v_ashrrev_i32_e32 v81, 31, v80
	v_ashrrev_i32_e32 v83, 31, v82
	v_add_u32_e32 v103, 0xffffff90, v65
	v_add_u32_e32 v109, s1, v120
	v_add_u32_e32 v110, s1, v121
	v_cmp_gt_u32_e64 s[58:59], 16, v65
	v_add_u32_e32 v114, s20, v120
	v_add_u32_e32 v120, s3, v120
	v_add_u32_e32 v121, s3, v121
	s_add_i32 s75, s74, 16
	v_mov_b32_e32 v1, v0
	v_subrev_u32_e32 v123, 48, v65
	v_add_u32_e32 v124, s24, v94
	v_add_u32_e32 v125, s74, v94
	s_xor_b64 s[82:83], s[60:61], -1
	v_add_u32_e32 v127, s25, v93
	v_add_u32_e32 v128, v128, v2
	v_add_u32_e32 v129, v129, v2
	v_add_u32_e32 v131, s25, v92
	v_add_u32_e32 v133, v133, v2
	v_add_u32_e32 v139, v108, v54
	v_add_u32_e32 v140, v88, v107
	v_add_u32_e32 v141, v55, v89
	v_add_u32_e32 v142, v55, v90
	v_add_u32_e32 v143, v55, v91
	v_add_u32_e32 v144, v144, v2
	v_add_u32_e32 v145, v145, v2
	v_add_u32_e32 v146, v55, v146
	v_add_u32_e32 v147, v55, v147
	v_add_u32_e32 v148, v55, v148
	v_mov_b64_e32 v[44:45], v[36:37]
	v_mov_b64_e32 v[40:41], v[36:37]
	v_mov_b64_e32 v[48:49], v[36:37]
	s_mov_b32 s81, 0
	s_waitcnt lgkmcnt(0)
	s_barrier
	v_readfirstlane_b32 s0, v197
	v_lshrrev_b32_e32 v140, 4, v65
	v_bfe_u32 v141, v65, 2, 2
	s_lshr_b32 s0, s0, 8
	v_lshl_add_u32 v140, v140, 3, v141
	s_lshl_b32 s0, s0, 7
	v_mul_u32_u24_e32 v140, 0x110, v140
	v_and_b32_e32 v141, 3, v65
	s_addk_i32 s0, 0x4400
	v_lshl_add_u32 v140, v141, 3, v140
	v_add_u32_e32 v140, s0, v140
	s_branch .LBB0_352

.LBB0_352:
	v_add_u32_e32 v155, s36, v124
	v_subrev_u32_e32 v2, 48, v155
	v_cmp_lt_i32_e32 vcc, -1, v2
	v_mov_b64_e32 v[90:91], 0x1a33cc00
	v_mov_b64_e32 v[92:93], 0x1a33cc00
	s_and_saveexec_b64 s[0:1], vcc
	v_add_u32_e32 v54, s36, v125
	v_subrev_u32_e32 v54, 64, v54
	v_mad_i64_i32 v[92:93], s[20:21], v54, s29, 0
	s_or_b64 exec, exec, s[0:1]
	v_cmp_gt_u32_e64 s[0:1], -16, v2
	v_cmp_lt_i32_e32 vcc, s86, v2
	s_or_b64 s[0:1], s[64:65], s[0:1]
	s_and_b64 s[20:21], vcc, s[0:1]
	s_and_saveexec_b64 s[0:1], s[20:21]
	v_mov_b32_e32 v54, s85
	v_cmp_gt_u32_e32 vcc, -16, v2
	s_nop 1
	v_cndmask_b32_e32 v2, v231, v54, vcc
	v_add3_u32 v2, v124, v2, s36
	v_subrev_u32_e32 v2, 48, v2
	v_mad_i64_i32 v[90:91], s[20:21], v2, s29, 0
	s_or_b64 exec, exec, s[0:1]
	s_add_i32 s20, s78, -1
	s_min_u32 s0, s20, 62
	s_lshl_b32 s0, s0, 6
	s_or_b32 s21, s0, s37
	v_or_b32_e32 v54, s21, v65
	v_ashrrev_i32_e32 v55, 31, v54
	v_lshlrev_b64 v[54:55], 7, v[54:55]
	v_lshl_add_u64 v[54:55], s[62:63], 0, v[54:55]
	global_load_dword v152, v[54:55], off
	v_add_u32_e32 v158, v70, v95
	s_waitcnt vmcnt(11)
	ds_write_b128 v134, v[4:7]
	s_waitcnt vmcnt(10)
	ds_write_b128 v158, v[8:11]
	s_waitcnt vmcnt(9)
	ds_write_b128 v135, v[12:15]
	s_waitcnt vmcnt(8)
	ds_write_b128 v136, v[20:23]
	s_cmp_eq_u32 s98, 0
	s_cbranch_scc1 .Lscan1_skip
	s_cmp_eq_u32 s81, 64
	s_cbranch_scc1 .Lscan1_skip
	v_mul_f32_e64 v198, v57, -v63
	v_mov_b32_e32 v199, v3
	s_nop 1
	v_mov_b32_dpp v199, v198 row_shr:1 row_mask:0xf bank_mask:0xf
	v_fma_f32 v198, v57, -v63, v199
	v_mov_b32_e32 v199, v3
	s_nop 0
	v_add_f32_dpp v198, v198, v198 row_shr:2 row_mask:0xf bank_mask:0xf bound_ctrl:1
	s_nop 1
	v_add_f32_dpp v198, v198, v198 row_shr:4 row_mask:0xf bank_mask:0xf bound_ctrl:1
	s_nop 1
	v_add_f32_dpp v198, v198, v198 row_shr:8 row_mask:0xf bank_mask:0xf bound_ctrl:1
	s_nop 1
	v_mov_b32_dpp v199, v198 row_bcast:15 row_mask:0xa bank_mask:0xf
	v_add_f32_e32 v198, v198, v199
	v_mov_b32_e32 v199, v3
	s_nop 1
	v_mov_b32_dpp v199, v198 row_bcast:31 row_mask:0xc bank_mask:0xf
	v_add_f32_e32 v198, v198, v199
	ds_write_b32 v104, v57
	ds_write_b32 v105, v198

.LBB0_360:
	v_add_u32_e32 v156, v106, v107
	ds_read_b128 v[160:163], v156 offset:34816
	ds_read_b128 v[164:167], v156 offset:34880
	ds_read_b128 v[168:171], v156 offset:17408
	ds_read_b128 v[172:175], v156 offset:17472
	ds_read_b128 v[176:179], v138
	ds_read_b128 v[180:183], v138 offset:64
	ds_read_b128 v[184:187], v138 offset:4352
	ds_read_b128 v[188:191], v138 offset:4416
	ds_read_b128 v[192:195], v156 offset:34944
	ds_read_b128 v[202:205], v156 offset:35008
	ds_read_b128 v[206:209], v156 offset:17536
	ds_read_b128 v[210:213], v156 offset:17600
	ds_read_b128 v[214:217], v138 offset:128
	ds_read_b128 v[236:239], v138 offset:192
	ds_read_b128 v[240:243], v138 offset:4480
	ds_read_b128 v[244:247], v138 offset:4544
	s_waitcnt lgkmcnt(11)
	v_mfma_f32_16x16x32_bf16 v[248:251], v[160:163], v[176:179], 0
	v_mfma_f32_16x16x32_bf16 v[176:179], v[168:171], v[176:179], 0
	s_waitcnt lgkmcnt(9)
	v_mfma_f32_16x16x32_bf16 v[160:163], v[160:163], v[184:187], 0
	v_mfma_f32_16x16x32_bf16 v[168:171], v[168:171], v[184:187], 0
	v_mfma_f32_16x16x32_bf16 v[184:187], v[164:167], v[180:183], v[248:251]
	v_mfma_f32_16x16x32_bf16 v[176:179], v[172:175], v[180:183], v[176:179]
	s_waitcnt lgkmcnt(8)
	v_mfma_f32_16x16x32_bf16 v[160:163], v[164:167], v[188:191], v[160:163]
	v_mfma_f32_16x16x32_bf16 v[164:167], v[172:175], v[188:191], v[168:171]
	s_waitcnt lgkmcnt(3)
	v_mfma_f32_16x16x32_bf16 v[168:171], v[192:195], v[214:217], v[184:187]
	v_mfma_f32_16x16x32_bf16 v[172:175], v[206:209], v[214:217], v[176:179]
	s_waitcnt lgkmcnt(1)
	v_mfma_f32_16x16x32_bf16 v[160:163], v[192:195], v[240:243], v[160:163]
	s_nop 0
	ds_read_b128 v[176:179], v139
	ds_read_b64_tr_b16 v[180:181], v140
	ds_read_b64_tr_b16 v[182:183], v140 offset:1088
	ds_read_b64_tr_b16 v[184:185], v140 offset:32
	ds_read_b64_tr_b16 v[186:187], v140 offset:1120
	ds_read_b64_tr_b16 v[188:189], v140 offset:64
	ds_read_b64_tr_b16 v[190:191], v140 offset:1152
	ds_read_b64_tr_b16 v[192:193], v140 offset:96
	ds_read_b64_tr_b16 v[194:195], v140 offset:1184
	v_mfma_f32_16x16x32_bf16 v[164:167], v[206:209], v[240:243], v[164:167]
	s_waitcnt lgkmcnt(9)
	v_mfma_f32_16x16x32_bf16 v[160:163], v[202:205], v[244:247], v[160:163]
	v_mfma_f32_16x16x32_bf16 v[168:171], v[202:205], v[236:239], v[168:171]
	v_mfma_f32_16x16x32_bf16 v[172:175], v[210:213], v[236:239], v[172:175]
	v_mfma_f32_16x16x32_bf16 v[164:167], v[210:213], v[244:247], v[164:167]
	ds_read_b32 v55, v109
	ds_read_b128 v[202:205], v127
	s_waitcnt lgkmcnt(0)
	v_pk_add_f32 v[198:199], v[54:55], v[202:203] op_sel:[1,0] op_sel_hi:[1,1] neg_lo:[0,1] neg_hi:[0,1]
	v_pk_add_f32 v[222:223], v[54:55], v[204:205] op_sel:[1,0] op_sel_hi:[1,1] neg_lo:[0,1] neg_hi:[0,1]
	v_pk_mul_f32 v[198:199], v[198:199], s[100:101]
	v_pk_mul_f32 v[222:223], v[222:223], s[100:101]
	v_exp_f32_e32 v198, v198
	v_exp_f32_e32 v199, v199
	v_exp_f32_e32 v222, v222
	v_exp_f32_e32 v223, v223
	v_pk_mul_f32 v[198:199], v[172:173], v[198:199]
	v_pk_mul_f32 v[222:223], v[174:175], v[222:223]
	v_cndmask_b32_e64 v198, v198, 0, s[42:43]
	v_cndmask_b32_e64 v199, 0, v199, s[44:45]
	v_cndmask_b32_e64 v222, v222, 0, s[46:47]
	v_cndmask_b32_e64 v223, v223, 0, s[48:49]
	v_cvt_pk_bf16_f32 v172, v198, v199
	v_cvt_pk_bf16_f32 v173, v222, v223
	ds_write_b64 v144, v[172:173]
	ds_read_b32 v89, v110
	ds_read_b128 v[172:175], v127
	v_mul_f32_e32 v55, 0x3fb8aa3b, v55
	v_exp_f32_e32 v154, v55
	s_waitcnt lgkmcnt(0)
	v_mul_f32_e32 v55, 0x3fb8aa3b, v89
	v_pk_add_f32 v[198:199], v[88:89], v[172:173] op_sel:[1,0] op_sel_hi:[1,1] neg_lo:[0,1] neg_hi:[0,1]
	v_pk_add_f32 v[222:223], v[88:89], v[174:175] op_sel:[1,0] op_sel_hi:[1,1] neg_lo:[0,1] neg_hi:[0,1]
	v_pk_mul_f32 v[198:199], v[198:199], s[100:101]
	v_pk_mul_f32 v[222:223], v[222:223], s[100:101]
	v_exp_f32_e32 v198, v198
	v_exp_f32_e32 v199, v199
	v_exp_f32_e32 v222, v222
	v_exp_f32_e32 v223, v223
	v_exp_f32_e32 v206, v55
	v_pk_mul_f32 v[198:199], v[164:165], v[198:199]
	v_pk_mul_f32 v[222:223], v[166:167], v[222:223]
	v_cndmask_b32_e64 v198, v198, 0, s[50:51]
	v_cndmask_b32_e64 v199, 0, v199, s[52:53]
	v_cndmask_b32_e64 v222, v222, 0, s[54:55]
	v_cndmask_b32_e64 v223, v223, 0, s[56:57]
	v_cvt_pk_bf16_f32 v164, v198, v199
	v_cvt_pk_bf16_f32 v165, v222, v223
	ds_write_b64 v145, v[164:165]
	v_mul_f32_e32 v54, 0x3fb8aa3b, v54
	v_exp_f32_e32 v54, v54
	ds_read_b64_tr_b16 v[164:165], v140 offset:8704
	ds_read_b64_tr_b16 v[166:167], v140 offset:9792
	v_add_u32_e32 v159, v108, v111
	ds_read_b128 v[172:175], v159
	v_pk_mul_f32 v[50:51], v[50:51], v[54:55] op_sel_hi:[1,0]
	v_pk_mul_f32 v[48:49], v[48:49], v[54:55] op_sel_hi:[1,0]
	v_pk_mul_f32 v[42:43], v[42:43], v[54:55] op_sel_hi:[1,0]
	v_pk_mul_f32 v[40:41], v[40:41], v[54:55] op_sel_hi:[1,0]
	v_pk_mul_f32 v[46:47], v[46:47], v[54:55] op_sel_hi:[1,0]
	v_pk_mul_f32 v[44:45], v[44:45], v[54:55] op_sel_hi:[1,0]
	v_pk_mul_f32 v[38:39], v[38:39], v[54:55] op_sel_hi:[1,0]
	v_pk_mul_f32 v[36:37], v[36:37], v[54:55] op_sel_hi:[1,0]
	v_mfma_f32_16x16x32_bf16 v[48:51], v[180:183], v[176:179], v[48:51]
	v_add_u32_e32 v54, v112, v113
	v_mfma_f32_16x16x32_bf16 v[40:43], v[184:187], v[176:179], v[40:43]
	v_mfma_f32_16x16x32_bf16 v[44:47], v[188:191], v[176:179], v[44:47]
	v_mfma_f32_16x16x32_bf16 v[36:39], v[192:195], v[176:179], v[36:39]
	ds_read_b64_tr_b16 v[176:177], v140 offset:8736
	ds_read_b64_tr_b16 v[178:179], v140 offset:9824
	s_waitcnt lgkmcnt(2)
	v_mfma_f32_16x16x32_bf16 v[48:51], v[164:167], v[172:175], v[48:51]
	ds_read_b64_tr_b16 v[164:165], v140 offset:8768
	ds_read_b64_tr_b16 v[166:167], v140 offset:9856
	ds_read_b64_tr_b16 v[180:181], v140 offset:8800
	ds_read_b64_tr_b16 v[182:183], v140 offset:9888
	s_waitcnt lgkmcnt(0)
	s_barrier
	s_waitcnt lgkmcnt(2)
	v_mfma_f32_16x16x32_bf16 v[40:43], v[176:179], v[172:175], v[40:43]
	ds_read_b128 v[176:179], v54
	ds_read_b128 v[184:187], v150
	v_add_u32_e32 v54, v112, v111
	s_waitcnt lgkmcnt(3)
	v_mfma_f32_16x16x32_bf16 v[44:47], v[164:167], v[172:175], v[44:47]
	ds_read_b128 v[164:167], v150 offset:2304
	ds_read_b128 v[188:191], v150 offset:64
	ds_read_b128 v[192:195], v54
	ds_read_b128 v[202:205], v150 offset:2368
	s_waitcnt lgkmcnt(6)
	v_mfma_f32_16x16x32_bf16 v[36:39], v[180:183], v[172:175], v[36:39]
	v_mul_f32_e64 v170, v170, v154
	v_mul_f32_e64 v171, v171, v154
	v_pk_mul_f32 v[168:169], v[168:169], v[154:155] op_sel_hi:[1,0]
	v_pk_mul_f32 v[162:163], v[162:163], v[206:207] op_sel_hi:[1,0]
	v_pk_mul_f32 v[160:161], v[160:161], v[206:207] op_sel_hi:[1,0]
	s_waitcnt lgkmcnt(4)
	v_mfma_f32_16x16x32_bf16 v[168:171], v[176:179], v[184:187], v[168:171]
	v_cvt_pk_bf16_f32 v54, v48, v49
	v_cvt_pk_bf16_f32 v55, v50, v51
	v_cvt_pk_bf16_f32 v172, v40, v41
	v_cvt_pk_bf16_f32 v173, v42, v43
	v_add_u32_e32 v157, 0x8800, v151
	s_waitcnt lgkmcnt(3)
	v_mfma_f32_16x16x32_bf16 v[160:163], v[176:179], v[164:167], v[160:163]
	ds_write2_b64 v157, v[54:55], v[172:173] offset1:4
	v_cvt_pk_bf16_f32 v54, v44, v45
	v_cvt_pk_bf16_f32 v55, v46, v47
	s_waitcnt lgkmcnt(2)
	v_mfma_f32_16x16x32_bf16 v[164:167], v[192:195], v[188:191], v[168:171]
	v_cmp_lt_i32_e32 vcc, v225, v220
	v_lshl_add_u64 v[92:93], v[86:87], 0, v[92:93]
	s_nop 0
	v_cvt_pk_bf16_f32 v168, v36, v37
	v_cvt_pk_bf16_f32 v169, v38, v39
	ds_write2_b64 v157, v[54:55], v[168:169] offset0:8 offset1:12
	v_cndmask_b32_e32 v54, v218, v225, vcc
	v_lshlrev_b32_e32 v153, 2, v54
	s_waitcnt vmcnt(9)
	v_lshlrev_b32_e32 v54, 16, v52
	v_and_b32_e32 v55, 0xffff0000, v52
	v_mul_f32_e32 v52, 0xbfb8aa3b, v54
	v_exp_f32_e32 v52, v52
	v_mul_f32_e32 v89, 0xbfb8aa3b, v55
	v_exp_f32_e32 v89, v89
	ds_read_b64 v[168:169], v128
	v_add_f32_e32 v52, 1.0, v52
	v_rcp_f32_e32 v170, v52
	v_add_f32_e32 v52, 1.0, v89
	v_rcp_f32_e32 v171, v52
	s_waitcnt lgkmcnt(0)
	v_lshlrev_b32_e32 v172, 16, v168
	v_and_b32_e32 v173, 0xffff0000, v168
	v_pk_fma_f32 v[164:165], v[0:1], v[172:173], v[164:165]
	v_pk_mul_f32 v[54:55], v[170:171], v[54:55]
	v_lshlrev_b32_e32 v52, 16, v53
	v_pk_mul_f32 v[164:165], v[54:55], v[164:165]
	v_and_b32_e32 v53, 0xffff0000, v53
	v_mul_f32_e32 v54, 0xbfb8aa3b, v52
	v_exp_f32_e32 v89, v54
	v_mul_f32_e32 v54, 0xbfb8aa3b, v53
	v_exp_f32_e32 v154, v54
	v_lshlrev_b32_e32 v168, 16, v169
	v_add_f32_e32 v89, 1.0, v89
	v_rcp_f32_e32 v170, v89
	v_add_f32_e32 v89, 1.0, v154
	v_rcp_f32_e32 v171, v89
	v_and_b32_e32 v169, 0xffff0000, v169
	v_pk_fma_f32 v[166:167], v[0:1], v[168:169], v[166:167]
	v_pk_mul_f32 v[54:55], v[164:165], v[164:165]
	v_pk_mul_f32 v[52:53], v[170:171], v[52:53]
	v_add_f32_e32 v54, v54, v55
	v_pk_mul_f32 v[166:167], v[52:53], v[166:167]
	v_cmp_lt_i32_e32 vcc, v226, v220
	v_pk_mul_f32 v[52:53], v[166:167], v[166:167]
	s_nop 0
	v_add_f32_e32 v52, v52, v54
	v_add_f32_e32 v89, v53, v52
	ds_bpermute_b32 v168, v153, v89
	v_cndmask_b32_e32 v154, v218, v226, vcc
	v_lshlrev_b32_e32 v154, 2, v154
	v_mfma_f32_16x16x32_bf16 v[52:55], v[192:195], v[202:205], v[160:163]
	s_waitcnt lgkmcnt(0)
	v_add_f32_e32 v89, v89, v168
	s_nop 0
	ds_bpermute_b32 v160, v154, v89
	v_cvt_pk_bf16_f32 v162, v164, v165
	v_cvt_pk_bf16_f32 v163, v166, v167
	global_store_dwordx2 v[92:93], v[162:163], off
	s_and_saveexec_b64 s[0:1], s[58:59]
	s_cbranch_execz .LBB0_362
	s_waitcnt lgkmcnt(0)
	v_add_f32_e32 v89, v89, v160
	ds_write_b32 v114, v89

.LBB0_364:
	s_or_b64 exec, exec, s[0:1]
	s_min_u32 s0, s20, 63
	v_lshl_or_b32 v54, s0, 6, v94
	v_add_u32_e32 v52, s74, v54
	s_waitcnt lgkmcnt(0)
	v_mad_i64_i32 v[52:53], s[0:1], v52, s29, v[86:87]
	v_add_u32_e32 v54, s75, v54
	v_mad_i64_i32 v[54:55], s[0:1], v54, s29, v[86:87]
	global_load_dwordx2 v[52:53], v[52:53], off
	s_nop 0
	global_load_dwordx2 v[84:85], v[54:55], off
	s_or_b32 s0, s81, 1
	s_cmp_gt_u32 s0, 64
	s_cbranch_scc1 .LBB0_351
	v_add_u32_e32 v54, 16, v155
	v_cmp_lt_i32_e32 vcc, -1, v54
	v_mov_b64_e32 v[90:91], 0x1a33cc00
	v_mov_b64_e32 v[92:93], 0x1a33cc00
	s_and_saveexec_b64 s[0:1], vcc
	v_add_u32_e32 v55, s36, v125
	v_mad_i64_i32 v[92:93], s[20:21], v55, s29, 0
	s_or_b64 exec, exec, s[0:1]
	v_cmp_gt_u32_e64 s[0:1], -16, v54
	v_cmp_lt_i32_e32 vcc, s86, v54
	s_or_b64 s[0:1], s[64:65], s[0:1]
	s_and_b64 s[20:21], vcc, s[0:1]
	s_and_saveexec_b64 s[0:1], s[20:21]
	v_mov_b32_e32 v55, s85
	v_cmp_gt_u32_e32 vcc, -16, v54
	s_nop 1
	v_cndmask_b32_e32 v54, v231, v55, vcc
	v_add_u32_e32 v54, v124, v54
	v_add3_u32 v54, v54, s36, 16
	v_mad_i64_i32 v[90:91], s[20:21], v54, s29, 0
	s_or_b64 exec, exec, s[0:1]
	s_min_u32 s0, s78, 62
	s_lshl_b32 s20, s0, 6
	s_add_i32 s20, s20, s37
	v_or_b32_e32 v54, s20, v65
	v_ashrrev_i32_e32 v55, 31, v54
	v_lshlrev_b64 v[54:55], 7, v[54:55]
	v_lshl_add_u64 v[54:55], s[62:63], 0, v[54:55]
	global_load_dword v57, v[54:55], off
	ds_write_b128 v134, v[16:19]
	ds_write_b128 v158, v[24:27]
	ds_write_b128 v135, v[28:31]
	ds_write_b128 v136, v[32:35]
	s_cmp_eq_u32 s98, 0
	s_cbranch_scc1 .Lscan2_skip
	s_waitcnt vmcnt(11)
	v_mul_f32_e64 v198, v152, -v63
	v_mov_b32_e32 v199, v3
	s_nop 1
	v_mov_b32_dpp v199, v198 row_shr:1 row_mask:0xf bank_mask:0xf
	v_fma_f32 v198, v152, -v63, v199
	v_mov_b32_e32 v199, v3
	s_nop 0
	v_add_f32_dpp v198, v198, v198 row_shr:2 row_mask:0xf bank_mask:0xf bound_ctrl:1
	s_nop 1
	v_add_f32_dpp v198, v198, v198 row_shr:4 row_mask:0xf bank_mask:0xf bound_ctrl:1
	s_nop 1
	v_add_f32_dpp v198, v198, v198 row_shr:8 row_mask:0xf bank_mask:0xf bound_ctrl:1
	s_nop 1
	v_mov_b32_dpp v199, v198 row_bcast:15 row_mask:0xa bank_mask:0xf
	v_add_f32_e32 v198, v198, v199
	v_mov_b32_e32 v199, v3
	s_nop 1
	v_mov_b32_dpp v199, v198 row_bcast:31 row_mask:0xc bank_mask:0xf
	v_add_f32_e32 v198, v198, v199
	ds_write_b32 v118, v152
	ds_write_b32 v119, v198

.LBB0_373:
	ds_read_b128 v[160:163], v156 offset:34816
	ds_read_b128 v[164:167], v156 offset:34880
	ds_read_b128 v[168:171], v156 offset:17408
	ds_read_b128 v[172:175], v156 offset:17472
	ds_read_b128 v[176:179], v138
	ds_read_b128 v[180:183], v138 offset:64
	ds_read_b128 v[184:187], v138 offset:4352
	ds_read_b128 v[188:191], v138 offset:4416
	ds_read_b128 v[192:195], v156 offset:34944
	ds_read_b128 v[202:205], v156 offset:35008
	ds_read_b128 v[206:209], v156 offset:17536
	ds_read_b128 v[210:213], v156 offset:17600
	ds_read_b128 v[214:217], v138 offset:128
	ds_read_b128 v[236:239], v138 offset:192
	ds_read_b128 v[240:243], v138 offset:4480
	ds_read_b128 v[244:247], v138 offset:4544
	s_waitcnt lgkmcnt(11)
	v_mfma_f32_16x16x32_bf16 v[248:251], v[160:163], v[176:179], 0
	v_mfma_f32_16x16x32_bf16 v[176:179], v[168:171], v[176:179], 0
	s_waitcnt lgkmcnt(9)
	v_mfma_f32_16x16x32_bf16 v[160:163], v[160:163], v[184:187], 0
	v_mfma_f32_16x16x32_bf16 v[168:171], v[168:171], v[184:187], 0
	v_mfma_f32_16x16x32_bf16 v[184:187], v[164:167], v[180:183], v[248:251]
	v_mfma_f32_16x16x32_bf16 v[176:179], v[172:175], v[180:183], v[176:179]
	s_waitcnt lgkmcnt(8)
	v_mfma_f32_16x16x32_bf16 v[160:163], v[164:167], v[188:191], v[160:163]
	v_mfma_f32_16x16x32_bf16 v[164:167], v[172:175], v[188:191], v[168:171]
	s_waitcnt lgkmcnt(3)
	v_mfma_f32_16x16x32_bf16 v[168:171], v[192:195], v[214:217], v[184:187]
	v_mfma_f32_16x16x32_bf16 v[172:175], v[206:209], v[214:217], v[176:179]
	s_waitcnt lgkmcnt(1)
	v_mfma_f32_16x16x32_bf16 v[160:163], v[192:195], v[240:243], v[160:163]
	s_nop 0
	ds_read_b128 v[176:179], v139
	ds_read_b64_tr_b16 v[180:181], v140
	ds_read_b64_tr_b16 v[182:183], v140 offset:1088
	ds_read_b64_tr_b16 v[184:185], v140 offset:32
	ds_read_b64_tr_b16 v[186:187], v140 offset:1120
	ds_read_b64_tr_b16 v[188:189], v140 offset:64
	ds_read_b64_tr_b16 v[190:191], v140 offset:1152
	ds_read_b64_tr_b16 v[192:193], v140 offset:96
	ds_read_b64_tr_b16 v[194:195], v140 offset:1184
	v_mfma_f32_16x16x32_bf16 v[164:167], v[206:209], v[240:243], v[164:167]
	v_mfma_f32_16x16x32_bf16 v[168:171], v[202:205], v[236:239], v[168:171]
	v_mfma_f32_16x16x32_bf16 v[172:175], v[210:213], v[236:239], v[172:175]
	s_waitcnt lgkmcnt(9)
	v_mfma_f32_16x16x32_bf16 v[160:163], v[202:205], v[244:247], v[160:163]
	v_mfma_f32_16x16x32_bf16 v[164:167], v[210:213], v[244:247], v[164:167]
	ds_read_b32 v88, v120
	ds_read_b128 v[202:205], v131
	s_waitcnt lgkmcnt(0)
	v_pk_add_f32 v[198:199], v[88:89], v[202:203] op_sel:[0,0] op_sel_hi:[0,1] neg_lo:[0,1] neg_hi:[0,1]
	v_pk_add_f32 v[222:223], v[88:89], v[204:205] op_sel:[0,0] op_sel_hi:[0,1] neg_lo:[0,1] neg_hi:[0,1]
	v_pk_mul_f32 v[198:199], v[198:199], s[100:101]
	v_pk_mul_f32 v[222:223], v[222:223], s[100:101]
	v_exp_f32_e32 v198, v198
	v_exp_f32_e32 v199, v199
	v_exp_f32_e32 v222, v222
	v_exp_f32_e32 v223, v223
	v_pk_mul_f32 v[198:199], v[172:173], v[198:199]
	v_pk_mul_f32 v[222:223], v[174:175], v[222:223]
	v_cndmask_b32_e64 v198, v198, 0, s[42:43]
	v_cndmask_b32_e64 v199, 0, v199, s[44:45]
	v_cndmask_b32_e64 v222, v222, 0, s[46:47]
	v_cndmask_b32_e64 v223, v223, 0, s[48:49]
	v_cvt_pk_bf16_f32 v54, v198, v199
	v_cvt_pk_bf16_f32 v55, v222, v223
	ds_write_b64 v144, v[54:55]
	ds_read_b32 v55, v121
	ds_read_b128 v[172:175], v131
	v_mul_f32_e32 v54, 0x3fb8aa3b, v88
	v_exp_f32_e32 v54, v54
	s_waitcnt lgkmcnt(0)
	v_mul_f32_e32 v88, 0x3fb8aa3b, v55
	v_pk_add_f32 v[198:199], v[54:55], v[172:173] op_sel:[1,0] op_sel_hi:[1,1] neg_lo:[0,1] neg_hi:[0,1]
	v_pk_add_f32 v[222:223], v[54:55], v[174:175] op_sel:[1,0] op_sel_hi:[1,1] neg_lo:[0,1] neg_hi:[0,1]
	v_pk_mul_f32 v[198:199], v[198:199], s[100:101]
	v_pk_mul_f32 v[222:223], v[222:223], s[100:101]
	v_exp_f32_e32 v198, v198
	v_exp_f32_e32 v199, v199
	v_exp_f32_e32 v222, v222
	v_exp_f32_e32 v223, v223
	v_exp_f32_e32 v88, v88
	v_pk_mul_f32 v[198:199], v[164:165], v[198:199]
	v_pk_mul_f32 v[222:223], v[166:167], v[222:223]
	v_cndmask_b32_e64 v198, v198, 0, s[50:51]
	v_cndmask_b32_e64 v199, 0, v199, s[52:53]
	v_cndmask_b32_e64 v222, v222, 0, s[54:55]
	v_cndmask_b32_e64 v223, v223, 0, s[56:57]
	v_cvt_pk_bf16_f32 v164, v198, v199
	v_cvt_pk_bf16_f32 v165, v222, v223
	ds_write_b64 v145, v[164:165]
	v_mul_f32_e32 v2, 0x3fb8aa3b, v2
	v_exp_f32_e32 v2, v2
	ds_read_b128 v[164:167], v159
	ds_read_b64_tr_b16 v[172:173], v140 offset:8704
	ds_read_b64_tr_b16 v[174:175], v140 offset:9792
	v_add_u32_e32 v55, v122, v111
	v_pk_mul_f32 v[50:51], v[50:51], v[2:3] op_sel_hi:[1,0]
	v_pk_mul_f32 v[48:49], v[48:49], v[2:3] op_sel_hi:[1,0]
	v_pk_mul_f32 v[42:43], v[42:43], v[2:3] op_sel_hi:[1,0]
	v_pk_mul_f32 v[40:41], v[40:41], v[2:3] op_sel_hi:[1,0]
	v_mfma_f32_16x16x32_bf16 v[48:51], v[180:183], v[176:179], v[48:51]
	v_mul_f32_e64 v46, v46, v2
	v_mul_f32_e64 v47, v47, v2
	v_pk_mul_f32 v[44:45], v[44:45], v[2:3] op_sel_hi:[1,0]
	v_pk_mul_f32 v[38:39], v[38:39], v[2:3] op_sel_hi:[1,0]
	v_pk_mul_f32 v[36:37], v[36:37], v[2:3] op_sel_hi:[1,0]
	v_mfma_f32_16x16x32_bf16 v[40:43], v[184:187], v[176:179], v[40:43]
	v_add_u32_e32 v2, v122, v113
	v_mfma_f32_16x16x32_bf16 v[44:47], v[188:191], v[176:179], v[44:47]
	v_mfma_f32_16x16x32_bf16 v[36:39], v[192:195], v[176:179], v[36:39]
	ds_read_b64_tr_b16 v[176:177], v140 offset:8736
	ds_read_b64_tr_b16 v[178:179], v140 offset:9824
	ds_read_b64_tr_b16 v[180:181], v140 offset:8768
	ds_read_b64_tr_b16 v[182:183], v140 offset:9856
	s_waitcnt lgkmcnt(4)
	v_mfma_f32_16x16x32_bf16 v[48:51], v[172:175], v[164:167], v[48:51]
	ds_read_b64_tr_b16 v[172:173], v140 offset:8800
	ds_read_b64_tr_b16 v[174:175], v140 offset:9888
	s_waitcnt lgkmcnt(0)
	s_barrier
	s_waitcnt lgkmcnt(2)
	v_mfma_f32_16x16x32_bf16 v[40:43], v[176:179], v[164:167], v[40:43]
	ds_read_b128 v[176:179], v2
	ds_read_b128 v[184:187], v55
	s_waitcnt lgkmcnt(3)
	v_mfma_f32_16x16x32_bf16 v[44:47], v[180:183], v[164:167], v[44:47]
	ds_read_b128 v[180:183], v150
	ds_read_b128 v[188:191], v150 offset:64
	ds_read_b128 v[192:195], v150 offset:2304
	ds_read_b128 v[202:205], v150 offset:2368
	s_waitcnt lgkmcnt(6)
	v_mfma_f32_16x16x32_bf16 v[36:39], v[172:175], v[164:167], v[36:39]
	v_mul_f32_e64 v166, v170, v54
	v_mul_f32_e64 v167, v171, v54
	v_pk_mul_f32 v[164:165], v[168:169], v[54:55] op_sel_hi:[1,0]
	v_pk_mul_f32 v[162:163], v[162:163], v[88:89] op_sel_hi:[1,0]
	v_pk_mul_f32 v[160:161], v[160:161], v[88:89] op_sel_hi:[1,0]
	v_cvt_pk_bf16_f32 v54, v48, v49
	v_cvt_pk_bf16_f32 v55, v50, v51
	v_cvt_pk_bf16_f32 v88, v40, v41
	v_cvt_pk_bf16_f32 v89, v42, v43
	ds_write2_b64 v157, v[54:55], v[88:89] offset1:4
	v_cvt_pk_bf16_f32 v54, v44, v45
	v_cvt_pk_bf16_f32 v55, v46, v47
	v_cvt_pk_bf16_f32 v88, v36, v37
	v_cvt_pk_bf16_f32 v89, v38, v39
	ds_write2_b64 v157, v[54:55], v[88:89] offset0:8 offset1:12
	s_waitcnt vmcnt(9)
	v_lshlrev_b32_e32 v54, 16, v52
	v_and_b32_e32 v55, 0xffff0000, v52
	v_mul_f32_e32 v2, 0xbfb8aa3b, v54
	v_exp_f32_e32 v2, v2
	v_mul_f32_e32 v52, 0xbfb8aa3b, v55
	v_exp_f32_e32 v52, v52
	s_waitcnt lgkmcnt(5)
	v_mfma_f32_16x16x32_bf16 v[164:167], v[176:179], v[180:183], v[164:167]
	ds_read_b64 v[88:89], v132
	v_add_f32_e32 v2, 1.0, v2
	v_rcp_f32_e32 v156, v2
	v_add_f32_e32 v2, 1.0, v52
	s_waitcnt lgkmcnt(4)
	v_mfma_f32_16x16x32_bf16 v[158:161], v[176:179], v[192:195], v[160:163]
	v_rcp_f32_e32 v157, v2
	v_lshlrev_b32_e32 v52, 16, v53
	v_and_b32_e32 v53, 0xffff0000, v53
	v_mfma_f32_16x16x32_bf16 v[162:165], v[184:187], v[188:191], v[164:167]
	v_mul_f32_e64 v54, v156, v54
	v_mul_f32_e64 v55, v157, v55
	v_mul_f32_e32 v2, 0xbfb8aa3b, v52
	v_exp_f32_e32 v2, v2
	s_waitcnt lgkmcnt(0)
	v_lshlrev_b32_e32 v166, 16, v88
	v_and_b32_e32 v167, 0xffff0000, v88
	s_nop 0
	v_pk_fma_f32 v[162:163], v[0:1], v[166:167], v[162:163]
	v_add_f32_e32 v2, 1.0, v2
	v_pk_mul_f32 v[156:157], v[54:55], v[162:163]
	v_mul_f32_e32 v54, 0xbfb8aa3b, v53
	v_exp_f32_e32 v88, v54
	v_rcp_f32_e32 v162, v2
	v_pk_mul_f32 v[54:55], v[156:157], v[156:157]
	v_cvt_pk_bf16_f32 v156, v156, v157
	v_add_f32_e32 v2, 1.0, v88
	v_rcp_f32_e32 v163, v2
	v_lshlrev_b32_e32 v88, 16, v89
	v_and_b32_e32 v89, 0xffff0000, v89
	v_pk_fma_f32 v[88:89], v[0:1], v[88:89], v[164:165]
	v_pk_mul_f32 v[52:53], v[162:163], v[52:53]
	v_add_f32_e32 v2, v54, v55
	v_pk_mul_f32 v[162:163], v[52:53], v[88:89]
	v_lshl_add_u64 v[92:93], v[86:87], 0, v[92:93]
	v_pk_mul_f32 v[52:53], v[162:163], v[162:163]
	v_cvt_pk_bf16_f32 v157, v162, v163
	v_add_f32_e32 v2, v52, v2
	v_add_f32_e32 v2, v53, v2
	ds_bpermute_b32 v88, v153, v2
	v_mfma_f32_16x16x32_bf16 v[52:55], v[184:187], v[202:205], v[158:161]
	global_store_dwordx2 v[92:93], v[156:157], off
	s_waitcnt lgkmcnt(0)
	v_add_f32_e32 v2, v2, v88
	ds_bpermute_b32 v88, v154, v2
	s_and_saveexec_b64 s[0:1], s[58:59]
	s_cbranch_execz .LBB0_375
	s_waitcnt lgkmcnt(0)
	v_add_f32_e32 v2, v2, v88
	ds_write_b32 v114, v2
